# K-fragment reads of both d-halves issued ahead of the V reloads so the first QK MFMA wait covers only K
# speedup vs baseline: 1.0002x; 1.0002x over previous
; #define LAS3 __attribute__((address_space(3)))
; #define ATT_SB() __builtin_amdgcn_sched_barrier(0)
; #define ATT_VREAD(buf, ks, vso) do { _Pragma("unroll") for (int d0 = 0; d0 < ND; ++d0) { const lds_cptr vq_ = ((d0 & 1) ? vpo : vpe) + (vso) + (d0 >> 1) * 8192 + (ks) * 2048; \
;       const s16x4 lo = vtr(vq_), hi4 = vtr(vq_ + 1024); \
;       buf[d0] = (bf16x8){lo[0], lo[1], lo[2], lo[3], hi4[0], hi4[1], hi4[2], hi4[3]}; } } while (0)
; #define ATT_PVK_RD(buf, ks, vp) do { _Pragma("unroll") for (int d0 = 0; d0 < ND; ++d0) { \
;       o[d0] = __builtin_amdgcn_mfma_f32_32x32x16_bf16(__builtin_bit_cast(bf16x8, pw[ks]), buf[d0], o[d0], 0, 0, 0); ATT_VREAD1(buf, d0, (ks) + 2, vp); ATT_SB(); } } while (0)
; template <int MODE>
; __device__ __forceinline__ void attn_unit(const Tensors& T0, int ureq, int b, int hh, int qblk, LAS3 char* shm, const bool dummy = false) {
;     ...
;     if (!(ATT_ABL == 4 && dummy)) { const int kso = (i & 3) * SLOTB; const int vp = ((i - 1) & 3) * SLOTB;
;       bf16x8 kf[8];
; #pragma unroll
;       for (int d0 = 0; d0 < 2; ++d0) { kf[2 * d0] = *(const LAS3 bf16x8*)(kp[d0] + kso); kf[2 * d0 + 1] = *(const LAS3 bf16x8*)(kp[d0] + kso + 4096); }
;       if (i > 0) { ATT_VREAD(vB, 1, vp); }
;       ATT_SB();
;       if (i > 0) { ATT_PVK_RD(vA, 0, vp); }
;       C0 = __builtin_amdgcn_mfma_f32_32x32x16_bf16(kf[0], qr[0], negm, 0, 0, 0); C1 = __builtin_amdgcn_mfma_f32_32x32x16_bf16(kf[1], qr[0], negm, 0, 0, 0);
.Lm1_head2_g0:
	ds_read_b128 v[100:103], v104
	ds_read_b128 v[206:209], v104 offset:4096
	v_mfma_f32_32x32x16_bf16 v[48:63], v[96:99], v[156:159], v[48:63]
	v_add_u32_e32 v205, s99, v193
	v_add_u32_e32 v242, s99, v190
	v_add_u32_e32 v104, s18, v195
	ds_read_b128 v[210:213], v104
	ds_read_b128 v[214:217], v104 offset:4096
	ds_read_b64_tr_b16 v[156:157], v205 offset:20480
	ds_read_b64_tr_b16 v[158:159], v205 offset:21504
	v_mfma_f32_32x32x16_bf16 v[64:79], v[96:99], v[152:155], v[64:79]
	ds_read_b64_tr_b16 v[152:153], v242 offset:20480
	ds_read_b64_tr_b16 v[154:155], v242 offset:21504
	ds_read_b64_tr_b16 v[218:219], v205 offset:18432
	ds_read_b64_tr_b16 v[220:221], v205 offset:19456
	s_add_i32 s96, s93, -2
	s_add_i32 s8, s95, 0xffffff67
	v_mfma_f32_32x32x16_bf16 v[32:47], v[96:99], v[148:151], v[32:47]
	ds_read_b64_tr_b16 v[148:149], v205 offset:28672
	ds_read_b64_tr_b16 v[150:151], v205 offset:29696
	ds_read_b64_tr_b16 v[222:223], v242 offset:18432
	ds_read_b64_tr_b16 v[224:225], v242 offset:19456
	s_cmpk_gt_i32 s8, 0xff66
	s_cselect_b64 vcc, -1, 0
	s_cmpk_gt_i32 s8, 0xd9
	s_cselect_b64 s[8:9], -1, 0
	v_mfma_f32_32x32x16_bf16 v[16:31], v[96:99], v[144:147], v[16:31]
	ds_read_b64_tr_b16 v[144:145], v242 offset:28672
	ds_read_b64_tr_b16 v[146:147], v242 offset:29696
	ds_read_b64_tr_b16 v[226:227], v205 offset:26624
	ds_read_b64_tr_b16 v[228:229], v205 offset:27648
	ds_read_b64_tr_b16 v[230:231], v242 offset:26624
	ds_read_b64_tr_b16 v[232:233], v242 offset:27648
	v_cndmask_b32_e64 v250, 0, v192, s[8:9]
	v_cndmask_b32_e32 v204, v191, v250, vcc
	v_add_u32_e32 v248, s18, v193
	v_add_u32_e32 v249, s18, v190
	v_cmp_neq_f32_e64 s[8:9], v204, v201
	v_add_u32_e32 v238, s18, v197
	s_and_b64 vcc, exec, s[8:9]
	s_cbranch_vccz .Lm1_negm_keep
	v_sub_f32_e32 v80, v204, v202
	v_mov_b32_e32 v201, v204
	v_mov_b32_e32 v81, v80
	v_mov_b32_e32 v82, v80
	v_mov_b32_e32 v83, v80
	v_mov_b32_e32 v84, v80
	v_mov_b32_e32 v85, v80
	v_mov_b32_e32 v86, v80
	v_mov_b32_e32 v87, v80
	v_mov_b32_e32 v88, v80
	v_mov_b32_e32 v89, v80
	v_mov_b32_e32 v90, v80
	v_mov_b32_e32 v91, v80
	v_mov_b32_e32 v92, v80
	v_mov_b32_e32 v93, v80
	v_mov_b32_e32 v94, v80
	v_mov_b32_e32 v95, v80
	s_nop 0
